# MoBA tile loop hand-interleaved fast path + vmcnt fix; GU K-loop SGPR-base LDS-DMA addressing; MODE1 merge prefetch
# speedup vs baseline: 1.0109x; 1.0109x over previous
.LBB0_346:
	s_lshl_b32 s12, s66, 2
	s_add_i32 s13, s12, 4
	s_and_b64 s[10:11], exec, s[52:53]
	s_cselect_b32 s69, s13, s67
	s_cmp_ge_u32 s12, s69
	s_cbranch_scc1 .LBB0_379
	ds_read_b128 v[32:35], v176
	ds_read_b128 v[48:51], v176 offset:512
	ds_read_b128 v[64:67], v176 offset:2080
	ds_read_b128 v[68:71], v176 offset:2592
	s_xor_b64 s[10:11], s[52:53], -1
	s_nor_b64 s[54:55], s[10:11], s[8:9]
	s_waitcnt lgkmcnt(3)
	v_mfma_f32_32x32x16_bf16 v[32:47], v[32:35], v[128:131], 0
	v_mov_b32_e32 v178, v173
	s_mov_b32 s70, s68
	s_mov_b32 s71, s65
	v_mov_b32_e32 v179, v172
	s_waitcnt lgkmcnt(2)
	v_mfma_f32_32x32x16_bf16 v[48:63], v[48:51], v[128:131], 0
	s_waitcnt lgkmcnt(1)
	v_mfma_f32_32x32x16_bf16 v[32:47], v[64:67], v[132:135], v[32:47]
	s_waitcnt lgkmcnt(0)
	v_mfma_f32_32x32x16_bf16 v[48:63], v[68:71], v[132:135], v[48:63]
	ds_read_b128 v[64:67], v176 offset:4160
	ds_read_b128 v[68:71], v176 offset:4672
	s_waitcnt lgkmcnt(1)
	v_mfma_f32_32x32x16_bf16 v[32:47], v[64:67], v[136:139], v[32:47]
	s_waitcnt lgkmcnt(0)
	v_mfma_f32_32x32x16_bf16 v[48:63], v[68:71], v[136:139], v[48:63]
	ds_read_b128 v[64:67], v176 offset:6240
	ds_read_b128 v[68:71], v176 offset:6752
	s_waitcnt lgkmcnt(1)
	v_mfma_f32_32x32x16_bf16 v[32:47], v[64:67], v[140:143], v[32:47]
	s_waitcnt lgkmcnt(0)
	v_mfma_f32_32x32x16_bf16 v[48:63], v[68:71], v[140:143], v[48:63]
	s_branch .LBB0_349
.Lm_fastA:
	ds_read_b128 v[196:199], v179
	ds_read_b128 v[200:203], v179 offset:512
	ds_read_b128 v[204:207], v179 offset:2080
	ds_read_b128 v[208:211], v179 offset:2592
	ds_read_b128 v[212:215], v179 offset:4160
	ds_read_b128 v[216:219], v179 offset:4672
	ds_read_b128 v[188:191], v179 offset:6240
	ds_read_b128 v[224:227], v179 offset:6752
	v_max_f32_e32 v144, v32, v32
	v_max_f32_e32 v145, v48, v48
	v_max3_f32 v144, v144, v33, v34
	v_max3_f32 v145, v145, v49, v50
	v_max3_f32 v144, v144, v35, v36
	s_waitcnt lgkmcnt(7)
	v_mfma_f32_32x32x16_bf16 v[64:79], v[196:199], v[128:131], 0
	v_max3_f32 v145, v145, v51, v52
	v_max3_f32 v144, v144, v37, v38
	v_max3_f32 v145, v145, v53, v54
	v_max3_f32 v144, v144, v39, v40
	s_waitcnt lgkmcnt(6)
	v_mfma_f32_32x32x16_bf16 v[80:95], v[200:203], v[128:131], 0
	v_max3_f32 v145, v145, v55, v56
	v_max3_f32 v144, v144, v41, v42
	v_max3_f32 v145, v145, v57, v58
	v_max3_f32 v144, v144, v43, v44
	s_waitcnt lgkmcnt(5)
	v_mfma_f32_32x32x16_bf16 v[64:79], v[204:207], v[132:135], v[64:79]
	v_max3_f32 v145, v145, v59, v60
	v_max3_f32 v144, v144, v45, v46
	v_max3_f32 v145, v145, v61, v62
	s_waitcnt lgkmcnt(4)
	v_mfma_f32_32x32x16_bf16 v[80:95], v[208:211], v[132:135], v[80:95]
	v_max3_f32 v144, v144, v47, v63
	v_max_f32_e32 v144, v144, v145
	v_mov_b32_e32 v145, v144
	s_nop 1
	v_permlane32_swap_b32_e32 v144, v145
	v_max_f32_e32 v145, v145, v145
	v_max_f32_e32 v144, v144, v144
	v_max_f32_e32 v144, v144, v145
	v_cmp_lt_f32_e32 vcc, s1, v144
	s_cbranch_vccnz .Lm_rareA
	s_waitcnt lgkmcnt(0)
	ds_read_b64_tr_b16 v[196:197], v178 offset:49920
	ds_read_b64_tr_b16 v[198:199], v178 offset:50432
	ds_read_b64_tr_b16 v[200:201], v178 offset:54016
	ds_read_b64_tr_b16 v[202:203], v178 offset:54528
	ds_read_b64_tr_b16 v[204:205], v178 offset:50944
	ds_read_b64_tr_b16 v[206:207], v178 offset:51456
	ds_read_b64_tr_b16 v[208:209], v178 offset:55040
	ds_read_b64_tr_b16 v[210:211], v178 offset:55552
	v_exp_f32_e32 v32, v32
	v_exp_f32_e32 v48, v48
	v_exp_f32_e32 v33, v33
	v_exp_f32_e32 v49, v49
	v_mfma_f32_32x32x16_bf16 v[64:79], v[212:215], v[136:139], v[64:79]
	v_exp_f32_e32 v34, v34
	v_exp_f32_e32 v50, v50
	v_exp_f32_e32 v35, v35
	v_exp_f32_e32 v51, v51
	v_exp_f32_e32 v36, v36
	v_exp_f32_e32 v52, v52
	v_mfma_f32_32x32x16_bf16 v[80:95], v[216:219], v[136:139], v[80:95]
	v_exp_f32_e32 v37, v37
	v_exp_f32_e32 v53, v53
	v_exp_f32_e32 v38, v38
	v_exp_f32_e32 v54, v54
	v_exp_f32_e32 v39, v39
	v_exp_f32_e32 v55, v55
	v_mfma_f32_32x32x16_bf16 v[64:79], v[188:191], v[140:143], v[64:79]
	v_exp_f32_e32 v40, v40
	v_exp_f32_e32 v56, v56
	v_exp_f32_e32 v41, v41
	v_exp_f32_e32 v57, v57
	v_exp_f32_e32 v42, v42
	v_exp_f32_e32 v58, v58
	v_mfma_f32_32x32x16_bf16 v[80:95], v[224:227], v[140:143], v[80:95]
	v_exp_f32_e32 v43, v43
	v_exp_f32_e32 v59, v59
	v_exp_f32_e32 v44, v44
	v_exp_f32_e32 v60, v60
	v_exp_f32_e32 v45, v45
	v_exp_f32_e32 v61, v61
	v_exp_f32_e32 v46, v46
	v_exp_f32_e32 v62, v62
	v_exp_f32_e32 v47, v47
	v_exp_f32_e32 v63, v63
	s_waitcnt lgkmcnt(7)
	ds_read_b64_tr_b16 v[212:213], v178 offset:51968
	ds_read_b64_tr_b16 v[214:215], v178 offset:52480
	ds_read_b64_tr_b16 v[216:217], v178 offset:56064
	ds_read_b64_tr_b16 v[218:219], v178 offset:56576
	ds_read_b64_tr_b16 v[188:189], v178 offset:52992
	ds_read_b64_tr_b16 v[190:191], v178 offset:53504
	ds_read_b64_tr_b16 v[224:225], v178 offset:57088
	ds_read_b64_tr_b16 v[226:227], v178 offset:57600
	v_pk_add_f32 v[238:239], v[52:53], v[36:37]
	v_pk_add_f32 v[240:241], v[48:49], v[32:33]
	v_pk_add_f32 v[242:243], v[54:55], v[38:39]
	v_pk_add_f32 v[244:245], v[50:51], v[34:35]
	v_cvt_pk_bf16_f32 v156, v32, v33
	v_cvt_pk_bf16_f32 v157, v34, v35
	v_cvt_pk_bf16_f32 v158, v36, v37
	v_cvt_pk_bf16_f32 v159, v38, v39
	v_cndmask_b32_e64 v156, 0, v156, s[6:7]
	v_cndmask_b32_e64 v157, 0, v157, s[6:7]
	v_cndmask_b32_e64 v158, 0, v158, s[6:7]
	v_cndmask_b32_e64 v159, 0, v159, s[6:7]
	v_pk_add_f32 v[246:247], v[58:59], v[42:43]
	v_pk_add_f32 v[248:249], v[56:57], v[40:41]
	s_waitcnt lgkmcnt(14)
	v_mfma_f32_32x32x16_bf16 v[16:31], v[156:159], v[196:199], v[16:31]
	v_pk_add_f32 v[242:243], v[244:245], v[242:243]
	v_pk_add_f32 v[238:239], v[240:241], v[238:239]
	v_cvt_pk_bf16_f32 v152, v40, v41
	v_cvt_pk_bf16_f32 v153, v42, v43
	v_cvt_pk_bf16_f32 v154, v44, v45
	v_cvt_pk_bf16_f32 v155, v46, v47
	s_waitcnt lgkmcnt(12)
	v_mfma_f32_32x32x16_bf16 v[0:15], v[156:159], v[200:203], v[0:15]
	v_cndmask_b32_e64 v152, 0, v152, s[6:7]
	v_cndmask_b32_e64 v153, 0, v153, s[6:7]
	v_cndmask_b32_e64 v154, 0, v154, s[6:7]
	v_cndmask_b32_e64 v155, 0, v155, s[6:7]
	v_pk_add_f32 v[240:241], v[60:61], v[44:45]
	v_pk_add_f32 v[244:245], v[62:63], v[46:47]
	s_waitcnt lgkmcnt(10)
	v_mfma_f32_32x32x16_bf16 v[16:31], v[152:155], v[204:207], v[16:31]
	v_pk_add_f32 v[248:249], v[248:249], v[238:239]
	v_pk_add_f32 v[246:247], v[246:247], v[242:243]
	v_cvt_pk_bf16_f32 v148, v48, v49
	v_cvt_pk_bf16_f32 v149, v50, v51
	v_cvt_pk_bf16_f32 v150, v52, v53
	v_cvt_pk_bf16_f32 v151, v54, v55
	s_waitcnt lgkmcnt(8)
	v_mfma_f32_32x32x16_bf16 v[0:15], v[152:155], v[208:211], v[0:15]
	v_cndmask_b32_e64 v148, 0, v148, s[6:7]
	v_cndmask_b32_e64 v149, 0, v149, s[6:7]
	v_cndmask_b32_e64 v150, 0, v150, s[6:7]
	v_cndmask_b32_e64 v151, 0, v151, s[6:7]
	v_pk_add_f32 v[182:183], v[240:241], v[248:249]
	v_pk_add_f32 v[180:181], v[244:245], v[246:247]
	s_waitcnt lgkmcnt(6)
	v_mfma_f32_32x32x16_bf16 v[16:31], v[148:151], v[212:215], v[16:31]
	v_pk_mov_b32 v[184:185], v[182:183], v[180:181] op_sel:[1,0]
	v_mov_b32_e32 v183, v181
	v_cvt_pk_bf16_f32 v144, v56, v57
	v_cvt_pk_bf16_f32 v145, v58, v59
	v_cvt_pk_bf16_f32 v146, v60, v61
	v_cvt_pk_bf16_f32 v147, v62, v63
	s_waitcnt lgkmcnt(4)
	v_mfma_f32_32x32x16_bf16 v[0:15], v[148:151], v[216:219], v[0:15]
	v_cndmask_b32_e64 v144, 0, v144, s[6:7]
	v_cndmask_b32_e64 v145, 0, v145, s[6:7]
	v_cndmask_b32_e64 v146, 0, v146, s[6:7]
	v_cndmask_b32_e64 v147, 0, v147, s[6:7]
	v_pk_add_f32 v[180:181], v[184:185], v[182:183]
	s_waitcnt lgkmcnt(2)
	v_mfma_f32_32x32x16_bf16 v[16:31], v[144:147], v[188:191], v[16:31]
	v_add_f32_e32 v181, v180, v181
	v_cndmask_b32_e64 v181, 0, v181, s[6:7]
	v_add_f32_e32 v177, v177, v181
	s_waitcnt lgkmcnt(0)
	v_mfma_f32_32x32x16_bf16 v[0:15], v[144:147], v[224:227], v[0:15]
	v_add_u32_e32 v180, 0, v178
	s_andn2_b64 s[8:9], exec, s[54:55]
	s_branch .Lm_halfB
.Lm_rareA:
	s_waitcnt lgkmcnt(0)
	v_mfma_f32_32x32x16_bf16 v[64:79], v[212:215], v[136:139], v[64:79]
	v_mfma_f32_32x32x16_bf16 v[80:95], v[216:219], v[136:139], v[80:95]
	v_mfma_f32_32x32x16_bf16 v[64:79], v[188:191], v[140:143], v[64:79]
	v_mfma_f32_32x32x16_bf16 v[80:95], v[224:227], v[140:143], v[80:95]
	s_branch .Lm_old358
.Lm_fastB:
	v_add_u32_e32 v251, 0x10100, v178
	ds_read_b128 v[196:199], v179 offset:8320
	ds_read_b128 v[200:203], v179 offset:8832
	ds_read_b128 v[204:207], v179 offset:10400
	ds_read_b128 v[208:211], v179 offset:10912
	ds_read_b128 v[212:215], v179 offset:12480
	ds_read_b128 v[216:219], v179 offset:12992
	ds_read_b128 v[188:191], v179 offset:14560
	ds_read_b128 v[224:227], v179 offset:15072
	v_max_f32_e32 v144, v64, v64
	v_max_f32_e32 v145, v80, v80
	v_max3_f32 v144, v144, v65, v66
	v_max3_f32 v145, v145, v81, v82
	v_max3_f32 v144, v144, v67, v68
	s_waitcnt lgkmcnt(7)
	v_mfma_f32_32x32x16_bf16 v[32:47], v[196:199], v[128:131], 0
	v_max3_f32 v145, v145, v83, v84
	v_max3_f32 v144, v144, v69, v70
	v_max3_f32 v145, v145, v85, v86
	v_max3_f32 v144, v144, v71, v72
	s_waitcnt lgkmcnt(6)
	v_mfma_f32_32x32x16_bf16 v[48:63], v[200:203], v[128:131], 0
	v_max3_f32 v145, v145, v87, v88
	v_max3_f32 v144, v144, v73, v74
	v_max3_f32 v145, v145, v89, v90
	v_max3_f32 v144, v144, v75, v76
	s_waitcnt lgkmcnt(5)
	v_mfma_f32_32x32x16_bf16 v[32:47], v[204:207], v[132:135], v[32:47]
	v_max3_f32 v145, v145, v91, v92
	v_max3_f32 v144, v144, v77, v78
	v_max3_f32 v145, v145, v93, v94
	s_waitcnt lgkmcnt(4)
	v_mfma_f32_32x32x16_bf16 v[48:63], v[208:211], v[132:135], v[48:63]
	v_max3_f32 v144, v144, v79, v95
	v_max_f32_e32 v144, v144, v145
	v_mov_b32_e32 v145, v144
	s_nop 1
	v_permlane32_swap_b32_e32 v144, v145
	v_max_f32_e32 v145, v145, v145
	v_max_f32_e32 v144, v144, v144
	v_max_f32_e32 v144, v144, v145
	v_cmp_lt_f32_e32 vcc, s1, v144
	s_cbranch_vccnz .Lm_rareB
	s_waitcnt lgkmcnt(0)
	ds_read_b64_tr_b16 v[196:197], v178 offset:58112
	ds_read_b64_tr_b16 v[198:199], v178 offset:58624
	ds_read_b64_tr_b16 v[200:201], v178 offset:62208
	ds_read_b64_tr_b16 v[202:203], v178 offset:62720
	ds_read_b64_tr_b16 v[204:205], v178 offset:59136
	ds_read_b64_tr_b16 v[206:207], v178 offset:59648
	ds_read_b64_tr_b16 v[208:209], v178 offset:63232
	ds_read_b64_tr_b16 v[210:211], v178 offset:63744
	v_exp_f32_e32 v64, v64
	v_exp_f32_e32 v80, v80
	v_exp_f32_e32 v65, v65
	v_exp_f32_e32 v81, v81
	v_mfma_f32_32x32x16_bf16 v[32:47], v[212:215], v[136:139], v[32:47]
	v_exp_f32_e32 v66, v66
	v_exp_f32_e32 v82, v82
	v_exp_f32_e32 v67, v67
	v_exp_f32_e32 v83, v83
	v_exp_f32_e32 v68, v68
	v_exp_f32_e32 v84, v84
	v_mfma_f32_32x32x16_bf16 v[48:63], v[216:219], v[136:139], v[48:63]
	v_exp_f32_e32 v69, v69
	v_exp_f32_e32 v85, v85
	v_exp_f32_e32 v70, v70
	v_exp_f32_e32 v86, v86
	v_exp_f32_e32 v71, v71
	v_exp_f32_e32 v87, v87
	v_mfma_f32_32x32x16_bf16 v[32:47], v[188:191], v[140:143], v[32:47]
	v_exp_f32_e32 v72, v72
	v_exp_f32_e32 v88, v88
	v_exp_f32_e32 v73, v73
	v_exp_f32_e32 v89, v89
	v_exp_f32_e32 v74, v74
	v_exp_f32_e32 v90, v90
	v_mfma_f32_32x32x16_bf16 v[48:63], v[224:227], v[140:143], v[48:63]
	v_exp_f32_e32 v75, v75
	v_exp_f32_e32 v91, v91
	v_exp_f32_e32 v76, v76
	v_exp_f32_e32 v92, v92
	v_exp_f32_e32 v77, v77
	v_exp_f32_e32 v93, v93
	v_exp_f32_e32 v78, v78
	v_exp_f32_e32 v94, v94
	v_exp_f32_e32 v79, v79
	v_exp_f32_e32 v95, v95
	s_waitcnt lgkmcnt(7)
	ds_read_b64_tr_b16 v[212:213], v178 offset:60160
	ds_read_b64_tr_b16 v[214:215], v178 offset:60672
	ds_read_b64_tr_b16 v[216:217], v178 offset:64256
	ds_read_b64_tr_b16 v[218:219], v178 offset:64768
	ds_read_b64_tr_b16 v[188:189], v178 offset:61184
	ds_read_b64_tr_b16 v[190:191], v178 offset:61696
	ds_read_b64_tr_b16 v[224:225], v178 offset:65280
	ds_read_b64_tr_b16 v[226:227], v251
	v_pk_add_f32 v[238:239], v[84:85], v[68:69]
	v_pk_add_f32 v[240:241], v[80:81], v[64:65]
	v_pk_add_f32 v[242:243], v[86:87], v[70:71]
	v_pk_add_f32 v[244:245], v[82:83], v[66:67]
	v_cvt_pk_bf16_f32 v156, v64, v65
	v_cvt_pk_bf16_f32 v157, v66, v67
	v_cvt_pk_bf16_f32 v158, v68, v69
	v_cvt_pk_bf16_f32 v159, v70, v71
	v_cndmask_b32_e64 v156, 0, v156, s[6:7]
	v_cndmask_b32_e64 v157, 0, v157, s[6:7]
	v_cndmask_b32_e64 v158, 0, v158, s[6:7]
	v_cndmask_b32_e64 v159, 0, v159, s[6:7]
	v_pk_add_f32 v[246:247], v[90:91], v[74:75]
	v_pk_add_f32 v[248:249], v[88:89], v[72:73]
	s_waitcnt lgkmcnt(14)
	v_mfma_f32_32x32x16_bf16 v[16:31], v[156:159], v[196:199], v[16:31]
	v_pk_add_f32 v[242:243], v[244:245], v[242:243]
	v_pk_add_f32 v[238:239], v[240:241], v[238:239]
	v_cvt_pk_bf16_f32 v152, v72, v73
	v_cvt_pk_bf16_f32 v153, v74, v75
	v_cvt_pk_bf16_f32 v154, v76, v77
	v_cvt_pk_bf16_f32 v155, v78, v79
	s_waitcnt lgkmcnt(12)
	v_mfma_f32_32x32x16_bf16 v[0:15], v[156:159], v[200:203], v[0:15]
	v_cndmask_b32_e64 v152, 0, v152, s[6:7]
	v_cndmask_b32_e64 v153, 0, v153, s[6:7]
	v_cndmask_b32_e64 v154, 0, v154, s[6:7]
	v_cndmask_b32_e64 v155, 0, v155, s[6:7]
	v_pk_add_f32 v[240:241], v[92:93], v[76:77]
	v_pk_add_f32 v[244:245], v[94:95], v[78:79]
	s_waitcnt lgkmcnt(10)
	v_mfma_f32_32x32x16_bf16 v[16:31], v[152:155], v[204:207], v[16:31]
	v_pk_add_f32 v[248:249], v[248:249], v[238:239]
	v_pk_add_f32 v[246:247], v[246:247], v[242:243]
	v_cvt_pk_bf16_f32 v148, v80, v81
	v_cvt_pk_bf16_f32 v149, v82, v83
	v_cvt_pk_bf16_f32 v150, v84, v85
	v_cvt_pk_bf16_f32 v151, v86, v87
	s_waitcnt lgkmcnt(8)
	v_mfma_f32_32x32x16_bf16 v[0:15], v[152:155], v[208:211], v[0:15]
	v_cndmask_b32_e64 v148, 0, v148, s[6:7]
	v_cndmask_b32_e64 v149, 0, v149, s[6:7]
	v_cndmask_b32_e64 v150, 0, v150, s[6:7]
	v_cndmask_b32_e64 v151, 0, v151, s[6:7]
	v_pk_add_f32 v[184:185], v[240:241], v[248:249]
	v_pk_add_f32 v[182:183], v[244:245], v[246:247]
	s_waitcnt lgkmcnt(6)
	v_mfma_f32_32x32x16_bf16 v[16:31], v[148:151], v[212:215], v[16:31]
	v_pk_mov_b32 v[186:187], v[184:185], v[182:183] op_sel:[1,0]
	v_mov_b32_e32 v185, v183
	v_cvt_pk_bf16_f32 v144, v88, v89
	v_cvt_pk_bf16_f32 v145, v90, v91
	v_cvt_pk_bf16_f32 v146, v92, v93
	v_cvt_pk_bf16_f32 v147, v94, v95
	s_waitcnt lgkmcnt(4)
	v_mfma_f32_32x32x16_bf16 v[0:15], v[148:151], v[216:219], v[0:15]
	v_cndmask_b32_e64 v144, 0, v144, s[6:7]
	v_cndmask_b32_e64 v145, 0, v145, s[6:7]
	v_cndmask_b32_e64 v146, 0, v146, s[6:7]
	v_cndmask_b32_e64 v147, 0, v147, s[6:7]
	v_pk_add_f32 v[182:183], v[186:187], v[184:185]
	s_waitcnt lgkmcnt(2)
	v_mfma_f32_32x32x16_bf16 v[16:31], v[144:147], v[188:191], v[16:31]
	v_add_f32_e32 v181, v182, v183
	v_cndmask_b32_e64 v181, 0, v181, s[6:7]
	v_add_f32_e32 v177, v177, v181
	s_waitcnt lgkmcnt(0)
	v_mfma_f32_32x32x16_bf16 v[0:15], v[144:147], v[224:227], v[0:15]
	v_add_u32_e32 v179, 0x4100, v179
	v_add_u32_e32 v178, 0x4000, v178
	s_add_i32 s71, s71, 2
	s_addk_i32 s70, 0x80
	s_branch .LBB0_349
.Lm_rareB:
	s_waitcnt lgkmcnt(0)
	v_mfma_f32_32x32x16_bf16 v[32:47], v[212:215], v[136:139], v[32:47]
	v_mfma_f32_32x32x16_bf16 v[48:63], v[216:219], v[136:139], v[48:63]
	v_mfma_f32_32x32x16_bf16 v[32:47], v[188:191], v[140:143], v[32:47]
	v_mfma_f32_32x32x16_bf16 v[48:63], v[224:227], v[140:143], v[48:63]
	s_branch .Lm_old373

.LBB0_349:
	s_add_i32 s8, s71, -1
	s_cmp_lt_u32 s8, s69
	s_cselect_b64 s[42:43], -1, 0
	s_cmp_ge_u32 s8, s69
	s_cbranch_scc1 .LBB0_351
	v_cmp_neq_f32_e32 vcc, 0, v174
	s_cbranch_vccnz .Lm_oldA
	s_cmp_le_u32 s70, s62
	s_cselect_b64 s[8:9], -1, 0
	s_or_b64 s[8:9], s[52:53], s[8:9]
	s_and_b64 vcc, exec, s[8:9]
	s_cbranch_vccnz .Lm_fastA
.Lm_oldA:
	v_add_u32_e32 v148, 0, v179
	ds_read_b128 v[196:199], v179
	ds_read_b128 v[200:203], v179 offset:512
	ds_read_b128 v[204:207], v179 offset:2080
	ds_read_b128 v[208:211], v179 offset:2592
	ds_read_b128 v[212:215], v179 offset:4160
	ds_read_b128 v[216:219], v179 offset:4672
	ds_read_b128 v[188:191], v179 offset:6240
	ds_read_b128 v[224:227], v179 offset:6752
	s_waitcnt lgkmcnt(6)
	v_mfma_f32_32x32x16_bf16 v[64:79], v[196:199], v[128:131], 0
	v_mfma_f32_32x32x16_bf16 v[80:95], v[200:203], v[128:131], 0
	s_waitcnt lgkmcnt(4)
	v_mfma_f32_32x32x16_bf16 v[64:79], v[204:207], v[132:135], v[64:79]
	v_mfma_f32_32x32x16_bf16 v[80:95], v[208:211], v[132:135], v[80:95]
	s_waitcnt lgkmcnt(2)
	v_mfma_f32_32x32x16_bf16 v[64:79], v[212:215], v[136:139], v[64:79]
	v_mfma_f32_32x32x16_bf16 v[80:95], v[216:219], v[136:139], v[80:95]
	s_waitcnt lgkmcnt(0)
	v_mfma_f32_32x32x16_bf16 v[64:79], v[188:191], v[140:143], v[64:79]
	v_mfma_f32_32x32x16_bf16 v[80:95], v[224:227], v[140:143], v[80:95]

.Lm_old358:
	v_max_f32_e32 v144, v144, v144
	v_max_f32_e32 v144, 0, v144
	v_exp_f32_e64 v145, -v144
	s_and_saveexec_b64 s[8:9], s[4:5]
	ds_write_b32 v168, v145
	s_or_b64 exec, exec, s[8:9]
	s_waitcnt lgkmcnt(0)
	v_add_u32_e32 v156, s33, v192
	v_add_f32_e32 v174, v174, v144
	v_pk_add_f32 v[32:33], v[32:33], v[144:145] op_sel_hi:[1,0] neg_lo:[0,1] neg_hi:[0,1]
	v_pk_add_f32 v[48:49], v[48:49], v[144:145] op_sel_hi:[1,0] neg_lo:[0,1] neg_hi:[0,1]
	v_pk_add_f32 v[34:35], v[34:35], v[144:145] op_sel_hi:[1,0] neg_lo:[0,1] neg_hi:[0,1]
	v_pk_add_f32 v[50:51], v[50:51], v[144:145] op_sel_hi:[1,0] neg_lo:[0,1] neg_hi:[0,1]
	v_pk_add_f32 v[36:37], v[36:37], v[144:145] op_sel_hi:[1,0] neg_lo:[0,1] neg_hi:[0,1]
	v_pk_add_f32 v[52:53], v[52:53], v[144:145] op_sel_hi:[1,0] neg_lo:[0,1] neg_hi:[0,1]
	v_pk_add_f32 v[38:39], v[38:39], v[144:145] op_sel_hi:[1,0] neg_lo:[0,1] neg_hi:[0,1]
	v_pk_add_f32 v[54:55], v[54:55], v[144:145] op_sel_hi:[1,0] neg_lo:[0,1] neg_hi:[0,1]
	v_pk_add_f32 v[40:41], v[40:41], v[144:145] op_sel_hi:[1,0] neg_lo:[0,1] neg_hi:[0,1]
	v_pk_add_f32 v[56:57], v[56:57], v[144:145] op_sel_hi:[1,0] neg_lo:[0,1] neg_hi:[0,1]
	v_pk_add_f32 v[42:43], v[42:43], v[144:145] op_sel_hi:[1,0] neg_lo:[0,1] neg_hi:[0,1]
	v_pk_add_f32 v[58:59], v[58:59], v[144:145] op_sel_hi:[1,0] neg_lo:[0,1] neg_hi:[0,1]
	v_pk_add_f32 v[44:45], v[44:45], v[144:145] op_sel_hi:[1,0] neg_lo:[0,1] neg_hi:[0,1]
	v_pk_add_f32 v[60:61], v[60:61], v[144:145] op_sel_hi:[1,0] neg_lo:[0,1] neg_hi:[0,1]
	v_pk_add_f32 v[46:47], v[46:47], v[144:145] op_sel_hi:[1,0] neg_lo:[0,1] neg_hi:[0,1]
	v_pk_add_f32 v[62:63], v[62:63], v[144:145] op_sel_hi:[1,0] neg_lo:[0,1] neg_hi:[0,1]
	v_mul_f32_e32 v177, v177, v145
	ds_read_b128 v[144:147], v156
	ds_read_b128 v[148:151], v156 offset:32
	ds_read_b128 v[152:155], v156 offset:64
	ds_read_b128 v[156:159], v156 offset:96
	s_waitcnt lgkmcnt(0)
	s_waitcnt lgkmcnt(3)
	v_pk_mul_f32 v[18:19], v[18:19], v[146:147]
	s_waitcnt lgkmcnt(2)
	v_pk_mul_f32 v[20:21], v[20:21], v[148:149]
	s_waitcnt lgkmcnt(1)
	v_pk_mul_f32 v[24:25], v[24:25], v[152:153]
	s_waitcnt lgkmcnt(0)
	v_pk_mul_f32 v[28:29], v[28:29], v[156:157]
	v_pk_mul_f32 v[30:31], v[30:31], v[158:159]
	v_pk_mul_f32 v[26:27], v[26:27], v[154:155]
	v_pk_mul_f32 v[22:23], v[22:23], v[150:151]
	v_pk_mul_f32 v[16:17], v[16:17], v[144:145]
	v_pk_mul_f32 v[12:13], v[12:13], v[156:157]
	v_pk_mul_f32 v[8:9], v[8:9], v[152:153]
	v_pk_mul_f32 v[4:5], v[4:5], v[148:149]
	v_pk_mul_f32 v[14:15], v[14:15], v[158:159]
	v_pk_mul_f32 v[10:11], v[10:11], v[154:155]
	v_pk_mul_f32 v[6:7], v[6:7], v[150:151]
	v_pk_mul_f32 v[2:3], v[2:3], v[146:147]
	v_pk_mul_f32 v[0:1], v[0:1], v[144:145]
.LBB0_361:
	ds_read_b64_tr_b16 v[196:197], v178 offset:49920
	ds_read_b64_tr_b16 v[198:199], v178 offset:50432
	ds_read_b64_tr_b16 v[200:201], v178 offset:54016
	ds_read_b64_tr_b16 v[202:203], v178 offset:54528
	ds_read_b64_tr_b16 v[204:205], v178 offset:50944
	ds_read_b64_tr_b16 v[206:207], v178 offset:51456
	ds_read_b64_tr_b16 v[208:209], v178 offset:55040
	ds_read_b64_tr_b16 v[210:211], v178 offset:55552
	ds_read_b64_tr_b16 v[212:213], v178 offset:51968
	ds_read_b64_tr_b16 v[214:215], v178 offset:52480
	ds_read_b64_tr_b16 v[216:217], v178 offset:56064
	ds_read_b64_tr_b16 v[218:219], v178 offset:56576
	v_exp_f32_e32 v32, v32
	v_exp_f32_e32 v48, v48
	v_exp_f32_e32 v33, v33
	v_exp_f32_e32 v49, v49
	v_exp_f32_e32 v34, v34
	v_exp_f32_e32 v50, v50
	v_exp_f32_e32 v35, v35
	v_exp_f32_e32 v51, v51
	v_exp_f32_e32 v36, v36
	v_exp_f32_e32 v52, v52
	v_exp_f32_e32 v37, v37
	v_exp_f32_e32 v53, v53
	v_exp_f32_e32 v38, v38
	v_exp_f32_e32 v54, v54
	v_exp_f32_e32 v39, v39
	v_exp_f32_e32 v55, v55
	v_exp_f32_e32 v40, v40
	v_exp_f32_e32 v56, v56
	v_exp_f32_e32 v41, v41
	v_exp_f32_e32 v42, v42
	v_exp_f32_e32 v58, v58
	v_exp_f32_e32 v43, v43
	v_exp_f32_e32 v59, v59
	v_exp_f32_e32 v57, v57
	v_exp_f32_e32 v44, v44
	v_exp_f32_e32 v60, v60
	v_exp_f32_e32 v45, v45
	v_exp_f32_e32 v61, v61
	v_exp_f32_e32 v46, v46
	v_exp_f32_e32 v62, v62
	v_exp_f32_e32 v47, v47
	v_exp_f32_e32 v63, v63
	v_pk_add_f32 v[152:153], v[52:53], v[36:37]
	v_pk_add_f32 v[154:155], v[48:49], v[32:33]
	v_pk_add_f32 v[156:157], v[54:55], v[38:39]
	v_pk_add_f32 v[158:159], v[50:51], v[34:35]
	v_pk_add_f32 v[148:149], v[58:59], v[42:43]
	v_pk_add_f32 v[150:151], v[56:57], v[40:41]
	v_pk_add_f32 v[156:157], v[158:159], v[156:157]
	v_pk_add_f32 v[152:153], v[154:155], v[152:153]
	v_pk_add_f32 v[144:145], v[60:61], v[44:45]
	v_pk_add_f32 v[146:147], v[62:63], v[46:47]
	v_pk_add_f32 v[150:151], v[150:151], v[152:153]
	v_pk_add_f32 v[148:149], v[148:149], v[156:157]
	v_pk_add_f32 v[182:183], v[144:145], v[150:151]
	v_pk_add_f32 v[180:181], v[146:147], v[148:149]
	v_cvt_pk_bf16_f32 v156, v32, v33
	v_pk_mov_b32 v[184:185], v[182:183], v[180:181] op_sel:[1,0]
	v_mov_b32_e32 v183, v181
	v_pk_add_f32 v[180:181], v[184:185], v[182:183]
	v_cndmask_b32_e64 v182, 0, 1, s[54:55]
	v_cvt_pk_bf16_f32 v152, v40, v41
	v_cvt_pk_bf16_f32 v148, v48, v49
	v_cvt_pk_bf16_f32 v144, v56, v57
	v_cvt_pk_bf16_f32 v157, v34, v35
	v_cvt_pk_bf16_f32 v153, v42, v43
	v_cvt_pk_bf16_f32 v149, v50, v51
	v_cvt_pk_bf16_f32 v145, v58, v59
	v_cvt_pk_bf16_f32 v158, v36, v37
	v_cvt_pk_bf16_f32 v154, v44, v45
	v_cvt_pk_bf16_f32 v150, v52, v53
	v_cvt_pk_bf16_f32 v146, v60, v61
	v_cvt_pk_bf16_f32 v159, v38, v39
	v_cvt_pk_bf16_f32 v155, v46, v47
	v_cvt_pk_bf16_f32 v151, v54, v55
	v_cvt_pk_bf16_f32 v147, v62, v63
	v_cmp_ne_u32_e64 s[8:9], 1, v182
	s_andn2_b64 vcc, exec, s[54:55]
	v_add_f32_e32 v181, v180, v181
	s_cbranch_vccnz .LBB0_363
	v_cndmask_b32_e64 v156, 0, v156, s[6:7]
	v_cndmask_b32_e64 v157, 0, v157, s[6:7]
	v_cndmask_b32_e64 v158, 0, v158, s[6:7]
	v_cndmask_b32_e64 v159, 0, v159, s[6:7]
	v_cndmask_b32_e64 v152, 0, v152, s[6:7]
	v_cndmask_b32_e64 v153, 0, v153, s[6:7]
	v_cndmask_b32_e64 v154, 0, v154, s[6:7]
	v_cndmask_b32_e64 v155, 0, v155, s[6:7]
	v_cndmask_b32_e64 v148, 0, v148, s[6:7]
	v_cndmask_b32_e64 v149, 0, v149, s[6:7]
	v_cndmask_b32_e64 v150, 0, v150, s[6:7]
	v_cndmask_b32_e64 v151, 0, v151, s[6:7]
	v_cndmask_b32_e64 v144, 0, v144, s[6:7]
	v_cndmask_b32_e64 v145, 0, v145, s[6:7]
	v_cndmask_b32_e64 v146, 0, v146, s[6:7]
	v_cndmask_b32_e64 v147, 0, v147, s[6:7]
	v_cndmask_b32_e64 v181, 0, v181, s[6:7]
.LBB0_363:
	v_add_u32_e32 v180, 0, v178
	s_waitcnt lgkmcnt(8)
	ds_read_b64_tr_b16 v[188:189], v178 offset:52992
	ds_read_b64_tr_b16 v[190:191], v178 offset:53504
	ds_read_b64_tr_b16 v[224:225], v178 offset:57088
	ds_read_b64_tr_b16 v[226:227], v178 offset:57600
	v_add_f32_e32 v177, v177, v181
	s_mov_b64 s[56:57], -1
	s_andn2_b64 vcc, exec, s[42:43]
	s_waitcnt lgkmcnt(14)
	v_mfma_f32_32x32x16_bf16 v[16:31], v[156:159], v[196:199], v[16:31]
	s_waitcnt lgkmcnt(12)
	v_mfma_f32_32x32x16_bf16 v[0:15], v[156:159], v[200:203], v[0:15]
	s_waitcnt lgkmcnt(10)
	v_mfma_f32_32x32x16_bf16 v[16:31], v[152:155], v[204:207], v[16:31]
	s_waitcnt lgkmcnt(8)
	v_mfma_f32_32x32x16_bf16 v[0:15], v[152:155], v[208:211], v[0:15]
	s_waitcnt lgkmcnt(6)
	v_mfma_f32_32x32x16_bf16 v[16:31], v[148:151], v[212:215], v[16:31]
	s_waitcnt lgkmcnt(4)
	v_mfma_f32_32x32x16_bf16 v[0:15], v[148:151], v[216:219], v[0:15]
	s_waitcnt lgkmcnt(2)
	v_mfma_f32_32x32x16_bf16 v[16:31], v[144:147], v[188:191], v[16:31]
	s_waitcnt lgkmcnt(0)
	v_mfma_f32_32x32x16_bf16 v[0:15], v[144:147], v[224:227], v[0:15]
	s_mov_b32 s10, 0
	s_mov_b32 s11, 0
	s_cbranch_vccnz .LBB0_348
.Lm_halfB:
	s_cmp_ge_u32 s71, s69
	s_cselect_b64 s[56:57], -1, 0
	s_and_b64 vcc, exec, s[56:57]
	s_cbranch_vccnz .LBB0_366
	v_cmp_neq_f32_e32 vcc, 0, v174
	s_cbranch_vccnz .Lm_oldB
	s_add_i32 s10, s70, 64
	s_cmp_le_u32 s10, s62
	s_cselect_b64 s[10:11], -1, 0
	s_or_b64 s[10:11], s[52:53], s[10:11]
	s_and_b64 vcc, exec, s[10:11]
	s_cbranch_vccnz .Lm_fastB
.Lm_oldB:
	v_add_u32_e32 v148, 0, v179
	ds_read_b128 v[196:199], v179 offset:8320
	ds_read_b128 v[200:203], v179 offset:8832
	ds_read_b128 v[204:207], v179 offset:10400
	ds_read_b128 v[208:211], v179 offset:10912
	ds_read_b128 v[212:215], v179 offset:12480
	ds_read_b128 v[216:219], v179 offset:12992
	ds_read_b128 v[188:191], v179 offset:14560
	ds_read_b128 v[224:227], v179 offset:15072
	s_waitcnt lgkmcnt(6)
	v_mfma_f32_32x32x16_bf16 v[32:47], v[196:199], v[128:131], 0
	v_mfma_f32_32x32x16_bf16 v[48:63], v[200:203], v[128:131], 0
	s_waitcnt lgkmcnt(4)
	v_mfma_f32_32x32x16_bf16 v[32:47], v[204:207], v[132:135], v[32:47]
	v_mfma_f32_32x32x16_bf16 v[48:63], v[208:211], v[132:135], v[48:63]
	s_waitcnt lgkmcnt(2)
	v_mfma_f32_32x32x16_bf16 v[32:47], v[212:215], v[136:139], v[32:47]
	v_mfma_f32_32x32x16_bf16 v[48:63], v[216:219], v[136:139], v[48:63]
	s_waitcnt lgkmcnt(0)
	v_mfma_f32_32x32x16_bf16 v[32:47], v[188:191], v[140:143], v[32:47]
	v_mfma_f32_32x32x16_bf16 v[48:63], v[224:227], v[140:143], v[48:63]

.Lm_old373:
	v_max_f32_e32 v144, v144, v144
	v_max_f32_e32 v144, 0, v144
	v_exp_f32_e64 v145, -v144
	s_and_saveexec_b64 s[10:11], s[4:5]
	ds_write_b32 v168, v145
	s_or_b64 exec, exec, s[10:11]
	s_waitcnt lgkmcnt(0)
	v_add_u32_e32 v156, s33, v192
	v_add_f32_e32 v174, v174, v144
	v_pk_add_f32 v[64:65], v[64:65], v[144:145] op_sel_hi:[1,0] neg_lo:[0,1] neg_hi:[0,1]
	v_pk_add_f32 v[80:81], v[80:81], v[144:145] op_sel_hi:[1,0] neg_lo:[0,1] neg_hi:[0,1]
	v_pk_add_f32 v[66:67], v[66:67], v[144:145] op_sel_hi:[1,0] neg_lo:[0,1] neg_hi:[0,1]
	v_pk_add_f32 v[82:83], v[82:83], v[144:145] op_sel_hi:[1,0] neg_lo:[0,1] neg_hi:[0,1]
	v_pk_add_f32 v[68:69], v[68:69], v[144:145] op_sel_hi:[1,0] neg_lo:[0,1] neg_hi:[0,1]
	v_pk_add_f32 v[84:85], v[84:85], v[144:145] op_sel_hi:[1,0] neg_lo:[0,1] neg_hi:[0,1]
	v_pk_add_f32 v[70:71], v[70:71], v[144:145] op_sel_hi:[1,0] neg_lo:[0,1] neg_hi:[0,1]
	v_pk_add_f32 v[86:87], v[86:87], v[144:145] op_sel_hi:[1,0] neg_lo:[0,1] neg_hi:[0,1]
	v_pk_add_f32 v[72:73], v[72:73], v[144:145] op_sel_hi:[1,0] neg_lo:[0,1] neg_hi:[0,1]
	v_pk_add_f32 v[88:89], v[88:89], v[144:145] op_sel_hi:[1,0] neg_lo:[0,1] neg_hi:[0,1]
	v_pk_add_f32 v[74:75], v[74:75], v[144:145] op_sel_hi:[1,0] neg_lo:[0,1] neg_hi:[0,1]
	v_pk_add_f32 v[90:91], v[90:91], v[144:145] op_sel_hi:[1,0] neg_lo:[0,1] neg_hi:[0,1]
	v_pk_add_f32 v[76:77], v[76:77], v[144:145] op_sel_hi:[1,0] neg_lo:[0,1] neg_hi:[0,1]
	v_pk_add_f32 v[92:93], v[92:93], v[144:145] op_sel_hi:[1,0] neg_lo:[0,1] neg_hi:[0,1]
	v_pk_add_f32 v[78:79], v[78:79], v[144:145] op_sel_hi:[1,0] neg_lo:[0,1] neg_hi:[0,1]
	v_pk_add_f32 v[94:95], v[94:95], v[144:145] op_sel_hi:[1,0] neg_lo:[0,1] neg_hi:[0,1]
	v_mul_f32_e32 v177, v177, v145
	ds_read_b128 v[144:147], v156
	ds_read_b128 v[148:151], v156 offset:32
	ds_read_b128 v[152:155], v156 offset:64
	ds_read_b128 v[156:159], v156 offset:96
	s_waitcnt lgkmcnt(0)
	s_waitcnt lgkmcnt(3)
	v_pk_mul_f32 v[18:19], v[18:19], v[146:147]
	s_waitcnt lgkmcnt(2)
	v_pk_mul_f32 v[20:21], v[20:21], v[148:149]
	s_waitcnt lgkmcnt(1)
	v_pk_mul_f32 v[24:25], v[24:25], v[152:153]
	s_waitcnt lgkmcnt(0)
	v_pk_mul_f32 v[28:29], v[28:29], v[156:157]
	v_pk_mul_f32 v[30:31], v[30:31], v[158:159]
	v_pk_mul_f32 v[26:27], v[26:27], v[154:155]
	v_pk_mul_f32 v[22:23], v[22:23], v[150:151]
	v_pk_mul_f32 v[16:17], v[16:17], v[144:145]
	v_pk_mul_f32 v[12:13], v[12:13], v[156:157]
	v_pk_mul_f32 v[8:9], v[8:9], v[152:153]
	v_pk_mul_f32 v[4:5], v[4:5], v[148:149]
	v_pk_mul_f32 v[14:15], v[14:15], v[158:159]
	v_pk_mul_f32 v[10:11], v[10:11], v[154:155]
	v_pk_mul_f32 v[6:7], v[6:7], v[150:151]
	v_pk_mul_f32 v[2:3], v[2:3], v[146:147]
	v_pk_mul_f32 v[0:1], v[0:1], v[144:145]
.LBB0_376:
	ds_read_b64_tr_b16 v[196:197], v180 offset:58112
	ds_read_b64_tr_b16 v[198:199], v180 offset:58624
	ds_read_b64_tr_b16 v[200:201], v180 offset:62208
	ds_read_b64_tr_b16 v[202:203], v180 offset:62720
	ds_read_b64_tr_b16 v[204:205], v180 offset:59136
	ds_read_b64_tr_b16 v[206:207], v180 offset:59648
	ds_read_b64_tr_b16 v[208:209], v180 offset:63232
	ds_read_b64_tr_b16 v[210:211], v180 offset:63744
	ds_read_b64_tr_b16 v[212:213], v180 offset:60160
	ds_read_b64_tr_b16 v[214:215], v180 offset:60672
	ds_read_b64_tr_b16 v[216:217], v180 offset:64256
	ds_read_b64_tr_b16 v[218:219], v180 offset:64768
	v_exp_f32_e32 v64, v64
	v_exp_f32_e32 v80, v80
	v_exp_f32_e32 v65, v65
	v_exp_f32_e32 v81, v81
	v_exp_f32_e32 v66, v66
	v_exp_f32_e32 v82, v82
	v_exp_f32_e32 v67, v67
	v_exp_f32_e32 v83, v83
	v_exp_f32_e32 v68, v68
	v_exp_f32_e32 v84, v84
	v_exp_f32_e32 v69, v69
	v_exp_f32_e32 v85, v85
	v_exp_f32_e32 v70, v70
	v_exp_f32_e32 v86, v86
	v_exp_f32_e32 v71, v71
	v_exp_f32_e32 v87, v87
	v_exp_f32_e32 v72, v72
	v_exp_f32_e32 v88, v88
	v_exp_f32_e32 v73, v73
	v_exp_f32_e32 v74, v74
	v_exp_f32_e32 v90, v90
	v_exp_f32_e32 v75, v75
	v_exp_f32_e32 v91, v91
	v_exp_f32_e32 v89, v89
	v_exp_f32_e32 v76, v76
	v_exp_f32_e32 v92, v92
	v_exp_f32_e32 v77, v77
	v_exp_f32_e32 v93, v93
	v_exp_f32_e32 v78, v78
	v_exp_f32_e32 v94, v94
	v_exp_f32_e32 v79, v79
	v_exp_f32_e32 v95, v95
	v_pk_add_f32 v[152:153], v[68:69], v[84:85]
	v_pk_add_f32 v[154:155], v[64:65], v[80:81]
	v_pk_add_f32 v[156:157], v[70:71], v[86:87]
	v_pk_add_f32 v[158:159], v[66:67], v[82:83]
	v_pk_add_f32 v[148:149], v[74:75], v[90:91]
	v_pk_add_f32 v[150:151], v[72:73], v[88:89]
	v_pk_add_f32 v[156:157], v[158:159], v[156:157]
	v_pk_add_f32 v[152:153], v[154:155], v[152:153]
	v_pk_add_f32 v[144:145], v[76:77], v[92:93]
	v_pk_add_f32 v[146:147], v[78:79], v[94:95]
	v_pk_add_f32 v[150:151], v[150:151], v[152:153]
	v_pk_add_f32 v[148:149], v[148:149], v[156:157]
	v_pk_add_f32 v[184:185], v[144:145], v[150:151]
	v_pk_add_f32 v[182:183], v[146:147], v[148:149]
	v_cvt_pk_bf16_f32 v156, v64, v65
	v_pk_mov_b32 v[186:187], v[184:185], v[182:183] op_sel:[1,0]
	v_mov_b32_e32 v185, v183
	v_pk_add_f32 v[182:183], v[186:187], v[184:185]
	v_cvt_pk_bf16_f32 v152, v72, v73
	v_cvt_pk_bf16_f32 v148, v80, v81
	v_cvt_pk_bf16_f32 v144, v88, v89
	v_cvt_pk_bf16_f32 v157, v66, v67
	v_cvt_pk_bf16_f32 v153, v74, v75
	v_cvt_pk_bf16_f32 v149, v82, v83
	v_cvt_pk_bf16_f32 v145, v90, v91
	v_cvt_pk_bf16_f32 v158, v68, v69
	v_cvt_pk_bf16_f32 v154, v76, v77
	v_cvt_pk_bf16_f32 v150, v84, v85
	v_cvt_pk_bf16_f32 v146, v92, v93
	v_cvt_pk_bf16_f32 v159, v70, v71
	v_cvt_pk_bf16_f32 v155, v78, v79
	v_cvt_pk_bf16_f32 v151, v86, v87
	v_cvt_pk_bf16_f32 v147, v94, v95
	s_and_b64 vcc, exec, s[8:9]
	v_add_f32_e32 v181, v182, v183
	s_cbranch_vccnz .LBB0_378
	v_cndmask_b32_e64 v156, 0, v156, s[6:7]
	v_cndmask_b32_e64 v157, 0, v157, s[6:7]
	v_cndmask_b32_e64 v158, 0, v158, s[6:7]
	v_cndmask_b32_e64 v159, 0, v159, s[6:7]
	v_cndmask_b32_e64 v152, 0, v152, s[6:7]
	v_cndmask_b32_e64 v153, 0, v153, s[6:7]
	v_cndmask_b32_e64 v154, 0, v154, s[6:7]
	v_cndmask_b32_e64 v155, 0, v155, s[6:7]
	v_cndmask_b32_e64 v148, 0, v148, s[6:7]
	v_cndmask_b32_e64 v149, 0, v149, s[6:7]
	v_cndmask_b32_e64 v150, 0, v150, s[6:7]
	v_cndmask_b32_e64 v151, 0, v151, s[6:7]
	v_cndmask_b32_e64 v144, 0, v144, s[6:7]
	v_cndmask_b32_e64 v145, 0, v145, s[6:7]
	v_cndmask_b32_e64 v146, 0, v146, s[6:7]
	v_cndmask_b32_e64 v147, 0, v147, s[6:7]
	v_cndmask_b32_e64 v181, 0, v181, s[6:7]
.LBB0_378:
	v_add_u32_e32 v238, 0x10100, v180
	s_waitcnt lgkmcnt(8)
	ds_read_b64_tr_b16 v[188:189], v180 offset:61184
	ds_read_b64_tr_b16 v[190:191], v180 offset:61696
	ds_read_b64_tr_b16 v[224:225], v180 offset:65280
	ds_read_b64_tr_b16 v[226:227], v238
	v_add_f32_e32 v177, v177, v181
	v_add_u32_e32 v179, 0x4100, v179
	s_add_i32 s10, s71, 2
	s_add_i32 s11, s70, 0x80
	v_add_u32_e32 v178, 0x4000, v178
	s_waitcnt lgkmcnt(14)
	v_mfma_f32_32x32x16_bf16 v[16:31], v[156:159], v[196:199], v[16:31]
	s_waitcnt lgkmcnt(12)
	v_mfma_f32_32x32x16_bf16 v[0:15], v[156:159], v[200:203], v[0:15]
	s_waitcnt lgkmcnt(10)
	v_mfma_f32_32x32x16_bf16 v[16:31], v[152:155], v[204:207], v[16:31]
	s_waitcnt lgkmcnt(8)
	v_mfma_f32_32x32x16_bf16 v[0:15], v[152:155], v[208:211], v[0:15]
	s_waitcnt lgkmcnt(6)
	v_mfma_f32_32x32x16_bf16 v[16:31], v[148:151], v[212:215], v[16:31]
	s_waitcnt lgkmcnt(4)
	v_mfma_f32_32x32x16_bf16 v[0:15], v[148:151], v[216:219], v[0:15]
	s_waitcnt lgkmcnt(2)
	v_mfma_f32_32x32x16_bf16 v[16:31], v[144:147], v[188:191], v[16:31]
	s_waitcnt lgkmcnt(0)
	v_mfma_f32_32x32x16_bf16 v[0:15], v[144:147], v[224:227], v[0:15]
	s_and_b64 vcc, exec, s[56:57]
	s_mov_b32 s70, s11
	s_mov_b32 s71, s10
	s_cbranch_vccz .LBB0_349

.LBB0_405:
	s_or_b64 exec, exec, s[10:11]
	s_waitcnt lgkmcnt(0)
	ds_read_b96 v[32:34], v160
	ds_read_b96 v[36:38], v160 offset:32
	v_readlane_b32 s10, v255, 41
	s_and_b32 s10, s89, s10
	s_or_b32 s10, s82, s10
	s_andn2_b64 vcc, exec, s[78:79]
	s_cbranch_vccnz .Lm1_nopf
	s_mov_b32 s11, s83
	s_lshl_b64 s[12:13], s[10:11], 11
	s_lshl_b64 s[14:15], s[10:11], 6
	s_add_u32 s14, s85, s14
	s_addc_u32 s15, s86, s15
	v_lshl_add_u64 v[42:43], v[148:149], 0, s[12:13]
	v_or_b32_e32 v40, s80, v159
	v_ashrrev_i32_e32 v41, 31, v40
	v_lshlrev_b64 v[44:45], s73, v[40:41]
	v_lshl_add_u64 v[44:45], v[44:45], 1, v[42:43]
	v_lshlrev_b64 v[46:47], s92, v[40:41]
	v_lshl_add_u64 v[46:47], v[46:47], 2, s[14:15]
	global_load_dword v60, v[46:47], off
	global_load_dwordx4 v[48:51], v[44:45], off
	v_or_b32_e32 v40, s80, v202
	v_ashrrev_i32_e32 v41, 31, v40
	v_lshlrev_b64 v[44:45], s73, v[40:41]
	v_lshl_add_u64 v[44:45], v[44:45], 1, v[42:43]
	v_lshlrev_b64 v[46:47], s92, v[40:41]
	v_lshl_add_u64 v[46:47], v[46:47], 2, s[14:15]
	global_load_dword v61, v[46:47], off
	global_load_dwordx4 v[52:55], v[44:45], off
	v_or_b32_e32 v40, s80, v203
	v_ashrrev_i32_e32 v41, 31, v40
	v_lshlrev_b64 v[44:45], s73, v[40:41]
	v_lshl_add_u64 v[44:45], v[44:45], 1, v[42:43]
	v_lshlrev_b64 v[46:47], s92, v[40:41]
	v_lshl_add_u64 v[46:47], v[46:47], 2, s[14:15]
	global_load_dword v62, v[46:47], off
	global_load_dwordx4 v[56:59], v[44:45], off
	v_or_b32_e32 v40, s80, v204
	v_ashrrev_i32_e32 v41, 31, v40
	v_lshlrev_b64 v[44:45], s73, v[40:41]
	v_lshl_add_u64 v[44:45], v[44:45], 1, v[42:43]
	v_lshlrev_b64 v[46:47], s92, v[40:41]
	v_lshl_add_u64 v[46:47], v[46:47], 2, s[14:15]
	global_load_dword v63, v[46:47], off
	global_load_dwordx4 v[218:221], v[44:45], off
.Lm1_nopf:
	s_waitcnt lgkmcnt(1)
	v_mul_f32_e32 v16, v16, v32
	v_mul_f32_e32 v0, v0, v32
	v_cvt_pk_bf16_f32 v16, v16, s0
	v_cvt_pk_bf16_f32 v0, v0, s0
	ds_write_b16 v161, v16
	ds_write_b16 v162, v0
	v_mul_f32_e32 v0, v17, v33
	v_cvt_pk_bf16_f32 v0, v0, s0
	ds_write_b16 v163, v0
	v_mul_f32_e32 v0, v1, v33
	v_cvt_pk_bf16_f32 v0, v0, s0
	ds_read_b32 v1, v167
	ds_write_b16 v164, v0
	v_mul_f32_e32 v0, v18, v34
	v_cvt_pk_bf16_f32 v0, v0, s0
	ds_write_b16 v165, v0
	v_mul_f32_e32 v0, v2, v34
	v_cvt_pk_bf16_f32 v0, v0, s0
	ds_write_b16 v166, v0
	s_waitcnt lgkmcnt(3)
	v_mul_f32_e32 v0, v19, v1
	v_cvt_pk_bf16_f32 v0, v0, s0
	ds_read_b32 v16, v176
	ds_read_b32 v17, v185
	ds_read_b32 v18, v198
	ds_write_b16 v168, v0
	v_mul_f32_e32 v0, v3, v1
	v_cvt_pk_bf16_f32 v0, v0, s0
	ds_write_b16 v169, v0
	v_mul_f32_e32 v0, v20, v36
	v_cvt_pk_bf16_f32 v0, v0, s0
	ds_write_b16 v170, v0
	v_mul_f32_e32 v0, v4, v36
	v_cvt_pk_bf16_f32 v0, v0, s0
	ds_write_b16 v171, v0
	v_mul_f32_e32 v0, v21, v37
	v_cvt_pk_bf16_f32 v0, v0, s0
	ds_write_b16 v172, v0
	v_mul_f32_e32 v0, v5, v37
	v_cvt_pk_bf16_f32 v0, v0, s0
	ds_write_b16 v173, v0
	v_mul_f32_e32 v0, v22, v38
	v_cvt_pk_bf16_f32 v0, v0, s0
	ds_write_b16 v174, v0
	v_mul_f32_e32 v0, v6, v38
	v_cvt_pk_bf16_f32 v0, v0, s0
	ds_write_b16 v175, v0
	s_waitcnt lgkmcnt(10)
	v_mul_f32_e32 v0, v23, v16
	v_cvt_pk_bf16_f32 v0, v0, s0
	ds_write_b16 v177, v0
	ds_read_b96 v[0:2], v160 offset:64
	ds_read_b96 v[4:6], v160 offset:96
	v_mul_f32_e32 v3, v7, v16
	v_cvt_pk_bf16_f32 v3, v3, s0
	ds_write_b16 v178, v3
	s_waitcnt lgkmcnt(2)
	v_mul_f32_e32 v3, v24, v0
	v_mul_f32_e32 v0, v8, v0
	v_cvt_pk_bf16_f32 v3, v3, s0
	v_cvt_pk_bf16_f32 v0, v0, s0
	ds_write_b16 v179, v3
	ds_write_b16 v180, v0
	v_mul_f32_e32 v0, v25, v1
	v_cvt_pk_bf16_f32 v0, v0, s0
	ds_write_b16 v181, v0
	v_mul_f32_e32 v0, v9, v1
	v_cvt_pk_bf16_f32 v0, v0, s0
	ds_write_b16 v182, v0
	v_mul_f32_e32 v0, v26, v2
	v_cvt_pk_bf16_f32 v0, v0, s0
	ds_write_b16 v183, v0
	v_mul_f32_e32 v0, v10, v2
	v_cvt_pk_bf16_f32 v0, v0, s0
	ds_write_b16 v184, v0
	v_mul_f32_e32 v0, v27, v17
	v_cvt_pk_bf16_f32 v0, v0, s0
	ds_write_b16 v186, v0
	v_mul_f32_e32 v0, v11, v17
	v_cvt_pk_bf16_f32 v0, v0, s0
	ds_write_b16 v187, v0
	s_waitcnt lgkmcnt(9)
	v_mul_f32_e32 v0, v28, v4
	v_cvt_pk_bf16_f32 v0, v0, s0
	ds_write_b16 v188, v0
	v_mul_f32_e32 v0, v12, v4
	v_cvt_pk_bf16_f32 v0, v0, s0
	ds_write_b16 v189, v0
	v_mul_f32_e32 v0, v29, v5
	v_cvt_pk_bf16_f32 v0, v0, s0
	ds_write_b16 v190, v0
	v_mul_f32_e32 v0, v13, v5
	v_cvt_pk_bf16_f32 v0, v0, s0
	ds_write_b16 v191, v0
	v_mul_f32_e32 v0, v30, v6
	v_cvt_pk_bf16_f32 v0, v0, s0
	ds_write_b16 v196, v0
	v_mul_f32_e32 v0, v14, v6
	v_cvt_pk_bf16_f32 v0, v0, s0
	ds_write_b16 v197, v0
	v_mul_f32_e32 v0, v31, v18
	v_cvt_pk_bf16_f32 v0, v0, s0
	ds_write_b16 v199, v0
	v_mul_f32_e32 v0, v15, v18
	v_cvt_pk_bf16_f32 v0, v0, s0
	s_mov_b32 s11, s83
	ds_write_b16 v200, v0
	v_or_b32_e32 v0, s80, v159
	s_lshl_b64 s[12:13], s[10:11], 11
	v_ashrrev_i32_e32 v1, 31, v0
	s_waitcnt lgkmcnt(0)
	v_lshl_add_u64 v[8:9], v[148:149], 0, s[12:13]
	v_lshlrev_b64 v[2:3], s73, v[0:1]
	v_lshl_add_u64 v[10:11], v[2:3], 1, v[8:9]
	v_lshlrev_b64 v[4:5], s92, v[0:1]
	ds_read_b128 v[0:3], v208
	ds_read_b32 v16, v201 offset:128
	s_lshl_b64 s[10:11], s[10:11], 6
	s_add_u32 s10, s85, s10
	s_addc_u32 s11, s86, s11
	s_andn2_b64 vcc, exec, s[78:79]
	v_lshl_add_u64 v[12:13], v[4:5], 2, s[10:11]
	s_cbranch_vccnz .LBB0_410
	s_waitcnt vmcnt(6)
	v_mov_b32_e32 v14, v60
	v_mov_b64_e32 v[4:5], v[48:49]
	v_mov_b64_e32 v[6:7], v[50:51]
	s_waitcnt lgkmcnt(0)
	v_max_f32_e32 v15, v16, v16
	s_mov_b64 s[14:15], 0
	s_mov_b64 s[12:13], 0
	v_max_f32_e32 v17, v14, v14
	v_max_f32_e32 v18, v17, v15
	v_sub_f32_e32 v14, v14, v18
	v_sub_f32_e32 v17, v16, v18
	v_exp_f32_e32 v15, v14
	v_exp_f32_e32 v14, v17
	s_nop 0
	v_add_f32_e32 v19, v15, v14
	s_and_saveexec_b64 s[16:17], s[6:7]
	v_log_f32_e32 v17, v19
	s_mov_b64 s[12:13], exec
	v_add_f32_e32 v17, v18, v17
	s_or_b64 exec, exec, s[16:17]
	v_rcp_f32_e32 v18, v19
	v_lshlrev_b32_e32 v22, 16, v4
	v_and_b32_e32 v23, 0xffff0000, v0
	v_lshlrev_b32_e32 v20, 16, v0
	v_pk_mul_f32 v[14:15], v[14:15], v[18:19] op_sel_hi:[1,0]
	v_and_b32_e32 v21, 0xffff0000, v4
	v_pk_mul_f32 v[18:19], v[14:15], v[22:23] op_sel:[1,0] op_sel_hi:[0,1]
	v_pk_fma_f32 v[18:19], v[14:15], v[20:21], v[18:19]
	v_lshlrev_b32_e32 v20, 16, v5
	v_and_b32_e32 v21, 0xffff0000, v1
	v_cvt_pk_bf16_f32 v4, v18, v19
	v_lshlrev_b32_e32 v18, 16, v1
	v_and_b32_e32 v19, 0xffff0000, v5
	v_pk_mul_f32 v[20:21], v[14:15], v[20:21] op_sel:[1,0] op_sel_hi:[0,1]
	v_pk_fma_f32 v[18:19], v[14:15], v[18:19], v[20:21]
	v_lshlrev_b32_e32 v20, 16, v6
	v_and_b32_e32 v21, 0xffff0000, v2
	v_cvt_pk_bf16_f32 v5, v18, v19
	v_lshlrev_b32_e32 v18, 16, v2
	v_and_b32_e32 v19, 0xffff0000, v6
	v_pk_mul_f32 v[20:21], v[14:15], v[20:21] op_sel:[1,0] op_sel_hi:[0,1]
	v_pk_fma_f32 v[18:19], v[14:15], v[18:19], v[20:21]
	v_lshlrev_b32_e32 v20, 16, v7
	v_and_b32_e32 v21, 0xffff0000, v3
	v_cvt_pk_bf16_f32 v6, v18, v19
	v_lshlrev_b32_e32 v18, 16, v3
	v_and_b32_e32 v19, 0xffff0000, v7
	v_pk_mul_f32 v[20:21], v[14:15], v[20:21] op_sel:[1,0] op_sel_hi:[0,1]
	v_pk_fma_f32 v[14:15], v[14:15], v[18:19], v[20:21]
	s_nop 0
	v_cvt_pk_bf16_f32 v7, v14, v15
	s_and_b64 vcc, exec, s[14:15]
	s_cbranch_vccnz .LBB0_411

.LBB0_417:
	s_or_b64 exec, exec, s[14:15]
	s_waitcnt lgkmcnt(1)
	ds_read_b128 v[0:3], v209
	s_waitcnt lgkmcnt(1)
	ds_read_b32 v16, v201 offset:160
	global_store_dwordx4 v[10:11], v[4:7], off
	s_and_b64 vcc, exec, s[78:79]
	s_nop 0
	v_or_b32_e32 v4, s80, v202
	v_ashrrev_i32_e32 v5, 31, v4
	v_lshlrev_b64 v[6:7], s73, v[4:5]
	v_lshlrev_b64 v[4:5], s92, v[4:5]
	v_lshl_add_u64 v[10:11], v[6:7], 1, v[8:9]
	v_lshl_add_u64 v[12:13], v[4:5], 2, s[10:11]
	s_cbranch_vccz .LBB0_422
	s_waitcnt vmcnt(5)
	v_mov_b32_e32 v14, v61
	v_mov_b64_e32 v[4:5], v[52:53]
	v_mov_b64_e32 v[6:7], v[54:55]
	s_waitcnt lgkmcnt(0)
	v_max_f32_e32 v15, v16, v16
	s_mov_b64 s[14:15], 0
	s_mov_b64 s[12:13], 0
	v_max_f32_e32 v17, v14, v14
	v_max_f32_e32 v19, v17, v15
	v_sub_f32_e32 v14, v14, v19
	v_sub_f32_e32 v17, v16, v19
	v_exp_f32_e32 v15, v14
	v_exp_f32_e32 v14, v17
	s_nop 0
	v_add_f32_e32 v18, v15, v14
	s_and_saveexec_b64 s[16:17], s[6:7]
	s_xor_b64 s[16:17], exec, s[16:17]
	v_log_f32_e32 v17, v18
	s_mov_b64 s[12:13], exec
	v_add_f32_e32 v17, v19, v17
	s_or_b64 exec, exec, s[16:17]
	v_rcp_f32_e32 v18, v18
	v_lshlrev_b32_e32 v22, 16, v4
	v_and_b32_e32 v23, 0xffff0000, v0
	v_lshlrev_b32_e32 v20, 16, v0
	v_pk_mul_f32 v[14:15], v[14:15], v[18:19] op_sel_hi:[1,0]
	v_and_b32_e32 v21, 0xffff0000, v4
	v_pk_mul_f32 v[18:19], v[14:15], v[22:23] op_sel:[1,0] op_sel_hi:[0,1]
	v_pk_fma_f32 v[18:19], v[14:15], v[20:21], v[18:19]
	v_lshlrev_b32_e32 v20, 16, v5
	v_and_b32_e32 v21, 0xffff0000, v1
	v_cvt_pk_bf16_f32 v4, v18, v19
	v_lshlrev_b32_e32 v18, 16, v1
	v_and_b32_e32 v19, 0xffff0000, v5
	v_pk_mul_f32 v[20:21], v[14:15], v[20:21] op_sel:[1,0] op_sel_hi:[0,1]
	v_pk_fma_f32 v[18:19], v[14:15], v[18:19], v[20:21]
	v_lshlrev_b32_e32 v20, 16, v6
	v_and_b32_e32 v21, 0xffff0000, v2
	v_cvt_pk_bf16_f32 v5, v18, v19
	v_lshlrev_b32_e32 v18, 16, v2
	v_and_b32_e32 v19, 0xffff0000, v6
	v_pk_mul_f32 v[20:21], v[14:15], v[20:21] op_sel:[1,0] op_sel_hi:[0,1]
	v_pk_fma_f32 v[18:19], v[14:15], v[18:19], v[20:21]
	v_lshlrev_b32_e32 v20, 16, v7
	v_and_b32_e32 v21, 0xffff0000, v3
	v_cvt_pk_bf16_f32 v6, v18, v19
	v_lshlrev_b32_e32 v18, 16, v3
	v_and_b32_e32 v19, 0xffff0000, v7
	v_pk_mul_f32 v[20:21], v[14:15], v[20:21] op_sel:[1,0] op_sel_hi:[0,1]
	v_pk_fma_f32 v[14:15], v[14:15], v[18:19], v[20:21]
	s_nop 0
	v_cvt_pk_bf16_f32 v7, v14, v15
	s_and_b64 vcc, exec, s[14:15]
	s_cbranch_vccnz .LBB0_423

.LBB0_429:
	s_or_b64 exec, exec, s[14:15]
	s_waitcnt lgkmcnt(1)
	ds_read_b128 v[0:3], v210
	s_waitcnt lgkmcnt(1)
	ds_read_b32 v16, v201 offset:192
	global_store_dwordx4 v[10:11], v[4:7], off
	s_and_b64 vcc, exec, s[78:79]
	s_nop 0
	v_or_b32_e32 v4, s80, v203
	v_ashrrev_i32_e32 v5, 31, v4
	v_lshlrev_b64 v[6:7], s73, v[4:5]
	v_lshlrev_b64 v[4:5], s92, v[4:5]
	v_lshl_add_u64 v[10:11], v[6:7], 1, v[8:9]
	v_lshl_add_u64 v[12:13], v[4:5], 2, s[10:11]
	s_cbranch_vccz .LBB0_434
	s_waitcnt vmcnt(4)
	v_mov_b32_e32 v14, v62
	v_mov_b64_e32 v[4:5], v[56:57]
	v_mov_b64_e32 v[6:7], v[58:59]
	s_waitcnt lgkmcnt(0)
	v_max_f32_e32 v15, v16, v16
	s_mov_b64 s[14:15], 0
	s_mov_b64 s[12:13], 0
	v_max_f32_e32 v17, v14, v14
	v_max_f32_e32 v19, v17, v15
	v_sub_f32_e32 v14, v14, v19
	v_sub_f32_e32 v17, v16, v19
	v_exp_f32_e32 v15, v14
	v_exp_f32_e32 v14, v17
	s_nop 0
	v_add_f32_e32 v18, v15, v14
	s_and_saveexec_b64 s[16:17], s[6:7]
	s_xor_b64 s[16:17], exec, s[16:17]
	v_log_f32_e32 v17, v18
	s_mov_b64 s[12:13], exec
	v_add_f32_e32 v17, v19, v17
	s_or_b64 exec, exec, s[16:17]
	v_rcp_f32_e32 v18, v18
	v_lshlrev_b32_e32 v22, 16, v4
	v_and_b32_e32 v23, 0xffff0000, v0
	v_lshlrev_b32_e32 v20, 16, v0
	v_pk_mul_f32 v[14:15], v[14:15], v[18:19] op_sel_hi:[1,0]
	v_and_b32_e32 v21, 0xffff0000, v4
	v_pk_mul_f32 v[18:19], v[14:15], v[22:23] op_sel:[1,0] op_sel_hi:[0,1]
	v_pk_fma_f32 v[18:19], v[14:15], v[20:21], v[18:19]
	v_lshlrev_b32_e32 v20, 16, v5
	v_and_b32_e32 v21, 0xffff0000, v1
	v_cvt_pk_bf16_f32 v4, v18, v19
	v_lshlrev_b32_e32 v18, 16, v1
	v_and_b32_e32 v19, 0xffff0000, v5
	v_pk_mul_f32 v[20:21], v[14:15], v[20:21] op_sel:[1,0] op_sel_hi:[0,1]
	v_pk_fma_f32 v[18:19], v[14:15], v[18:19], v[20:21]
	v_lshlrev_b32_e32 v20, 16, v6
	v_and_b32_e32 v21, 0xffff0000, v2
	v_cvt_pk_bf16_f32 v5, v18, v19
	v_lshlrev_b32_e32 v18, 16, v2
	v_and_b32_e32 v19, 0xffff0000, v6
	v_pk_mul_f32 v[20:21], v[14:15], v[20:21] op_sel:[1,0] op_sel_hi:[0,1]
	v_pk_fma_f32 v[18:19], v[14:15], v[18:19], v[20:21]
	v_lshlrev_b32_e32 v20, 16, v7
	v_and_b32_e32 v21, 0xffff0000, v3
	v_cvt_pk_bf16_f32 v6, v18, v19
	v_lshlrev_b32_e32 v18, 16, v3
	v_and_b32_e32 v19, 0xffff0000, v7
	v_pk_mul_f32 v[20:21], v[14:15], v[20:21] op_sel:[1,0] op_sel_hi:[0,1]
	v_pk_fma_f32 v[14:15], v[14:15], v[18:19], v[20:21]
	s_nop 0
	v_cvt_pk_bf16_f32 v7, v14, v15
	s_and_b64 vcc, exec, s[14:15]
	s_cbranch_vccnz .LBB0_435

.LBB0_441:
	s_or_b64 exec, exec, s[14:15]
	s_waitcnt lgkmcnt(1)
	v_or_b32_e32 v0, s80, v204
	v_ashrrev_i32_e32 v1, 31, v0
	global_store_dwordx4 v[10:11], v[4:7], off
	v_lshlrev_b64 v[2:3], s73, v[0:1]
	v_lshl_add_u64 v[8:9], v[2:3], 1, v[8:9]
	v_lshlrev_b64 v[4:5], s92, v[0:1]
	ds_read_b128 v[0:3], v211
	ds_read_b32 v14, v201 offset:224
	v_lshl_add_u64 v[10:11], v[4:5], 2, s[10:11]
	s_and_b64 vcc, exec, s[78:79]
	s_cbranch_vccz .LBB0_446
	s_waitcnt vmcnt(3)
	v_mov_b32_e32 v12, v63
	v_mov_b64_e32 v[4:5], v[218:219]
	v_mov_b64_e32 v[6:7], v[220:221]
	s_waitcnt lgkmcnt(0)
	v_max_f32_e32 v13, v14, v14
	s_mov_b64 s[12:13], 0
	s_mov_b64 s[10:11], 0
	v_max_f32_e32 v15, v12, v12
	v_max_f32_e32 v17, v15, v13
	v_sub_f32_e32 v12, v12, v17
	v_sub_f32_e32 v15, v14, v17
	v_exp_f32_e32 v13, v12
	v_exp_f32_e32 v12, v15
	s_nop 0
	v_add_f32_e32 v16, v13, v12
	s_and_saveexec_b64 s[14:15], s[6:7]
	s_xor_b64 s[14:15], exec, s[14:15]
	v_log_f32_e32 v15, v16
	s_mov_b64 s[10:11], exec
	v_add_f32_e32 v15, v17, v15
	s_or_b64 exec, exec, s[14:15]
	v_rcp_f32_e32 v16, v16
	v_lshlrev_b32_e32 v20, 16, v4
	v_and_b32_e32 v21, 0xffff0000, v0
	v_lshlrev_b32_e32 v18, 16, v0
	v_pk_mul_f32 v[12:13], v[12:13], v[16:17] op_sel_hi:[1,0]
	v_and_b32_e32 v19, 0xffff0000, v4
	v_pk_mul_f32 v[16:17], v[12:13], v[20:21] op_sel:[1,0] op_sel_hi:[0,1]
	v_pk_fma_f32 v[16:17], v[12:13], v[18:19], v[16:17]
	v_lshlrev_b32_e32 v18, 16, v5
	v_and_b32_e32 v19, 0xffff0000, v1
	v_cvt_pk_bf16_f32 v4, v16, v17
	v_lshlrev_b32_e32 v16, 16, v1
	v_and_b32_e32 v17, 0xffff0000, v5
	v_pk_mul_f32 v[18:19], v[12:13], v[18:19] op_sel:[1,0] op_sel_hi:[0,1]
	v_pk_fma_f32 v[16:17], v[12:13], v[16:17], v[18:19]
	v_lshlrev_b32_e32 v18, 16, v6
	v_and_b32_e32 v19, 0xffff0000, v2
	v_cvt_pk_bf16_f32 v5, v16, v17
	v_lshlrev_b32_e32 v16, 16, v2
	v_and_b32_e32 v17, 0xffff0000, v6
	v_pk_mul_f32 v[18:19], v[12:13], v[18:19] op_sel:[1,0] op_sel_hi:[0,1]
	v_pk_fma_f32 v[16:17], v[12:13], v[16:17], v[18:19]
	v_lshlrev_b32_e32 v18, 16, v7
	v_and_b32_e32 v19, 0xffff0000, v3
	v_cvt_pk_bf16_f32 v6, v16, v17
	v_lshlrev_b32_e32 v16, 16, v3
	v_and_b32_e32 v17, 0xffff0000, v7
	v_pk_mul_f32 v[18:19], v[12:13], v[18:19] op_sel:[1,0] op_sel_hi:[0,1]
	v_pk_fma_f32 v[12:13], v[12:13], v[16:17], v[18:19]
	s_nop 0
	v_cvt_pk_bf16_f32 v7, v12, v13
	s_and_b64 vcc, exec, s[12:13]
	s_cbranch_vccnz .LBB0_447

.LBB0_574:
	s_add_u32 s34, s30, 0xfffc0080
	s_addc_u32 s35, s31, -1
	s_add_i32 s54, 0, 0x10000
	s_cmp_eq_u32 s53, 12
	s_cselect_b32 s37, s25, s35
	s_cselect_b32 s36, s49, s34
	v_add_u32_e32 v138, s54, v141
	s_cselect_b32 s35, s23, s52
	s_cselect_b32 s34, s50, s51
	s_add_i32 s61, 0, 0x14000
	ds_read_b128 v[144:147], v138
	ds_read_b128 v[148:151], v138 offset:1024
	ds_read_b128 v[152:155], v138 offset:2048
	ds_read_b128 v[156:159], v138 offset:3072
	v_add_u32_e32 v138, s61, v141
	ds_read_b128 v[160:163], v138
	ds_read_b128 v[164:167], v138 offset:1024
	ds_read_b128 v[168:171], v138 offset:2048
	ds_read_b128 v[172:175], v138 offset:3072
	s_add_i32 m0, s40, 0xc000
	ds_read_b128 v[176:179], v143
	ds_read_b128 v[180:183], v143 offset:1024
	ds_read_b128 v[184:187], v143 offset:2048
	ds_read_b128 v[188:191], v143 offset:3072
	ds_read_b128 v[196:199], v143 offset:4096
	ds_read_b128 v[200:203], v143 offset:5120
	ds_read_b128 v[204:207], v143 offset:6144
	ds_read_b128 v[208:211], v143 offset:7168
	global_load_lds_dwordx4 v136, s[30:31]
	s_add_i32 m0, s40, 0xe000
	s_nop 0
	global_load_lds_dwordx4 v134, s[30:31]
	s_waitcnt vmcnt(8)
	s_waitcnt lgkmcnt(0)
	s_barrier
	s_setprio 1
	s_waitcnt lgkmcnt(0)
	v_mfma_f32_16x16x32_bf16 v[124:127], v[144:147], v[176:179], v[124:127]
	v_mfma_f32_16x16x32_bf16 v[120:123], v[152:155], v[176:179], v[120:123]
	v_mfma_f32_16x16x32_bf16 v[108:111], v[144:147], v[184:187], v[108:111]
	v_mfma_f32_16x16x32_bf16 v[104:107], v[152:155], v[184:187], v[104:107]
	v_mfma_f32_16x16x32_bf16 v[92:95], v[144:147], v[196:199], v[92:95]
	v_mfma_f32_16x16x32_bf16 v[88:91], v[152:155], v[196:199], v[88:91]
	v_mfma_f32_16x16x32_bf16 v[76:79], v[144:147], v[204:207], v[76:79]
	v_mfma_f32_16x16x32_bf16 v[72:75], v[152:155], v[204:207], v[72:75]
	v_mfma_f32_16x16x32_bf16 v[124:127], v[148:151], v[180:183], v[124:127]
	v_mfma_f32_16x16x32_bf16 v[120:123], v[156:159], v[180:183], v[120:123]
	v_mfma_f32_16x16x32_bf16 v[108:111], v[148:151], v[188:191], v[108:111]
	v_mfma_f32_16x16x32_bf16 v[104:107], v[156:159], v[188:191], v[104:107]
	v_mfma_f32_16x16x32_bf16 v[92:95], v[148:151], v[200:203], v[92:95]
	v_mfma_f32_16x16x32_bf16 v[88:91], v[156:159], v[200:203], v[88:91]
	v_mfma_f32_16x16x32_bf16 v[76:79], v[148:151], v[208:211], v[76:79]
	v_mfma_f32_16x16x32_bf16 v[72:75], v[156:159], v[208:211], v[72:75]
	s_setprio 0
	s_setprio 1
	v_mfma_f32_16x16x32_bf16 v[116:119], v[160:163], v[176:179], v[116:119]
	v_mfma_f32_16x16x32_bf16 v[112:115], v[168:171], v[176:179], v[112:115]
	v_mfma_f32_16x16x32_bf16 v[100:103], v[160:163], v[184:187], v[100:103]
	v_mfma_f32_16x16x32_bf16 v[96:99], v[168:171], v[184:187], v[96:99]
	v_mfma_f32_16x16x32_bf16 v[84:87], v[160:163], v[196:199], v[84:87]
	v_mfma_f32_16x16x32_bf16 v[80:83], v[168:171], v[196:199], v[80:83]
	v_mfma_f32_16x16x32_bf16 v[68:71], v[160:163], v[204:207], v[68:71]
	v_mfma_f32_16x16x32_bf16 v[64:67], v[168:171], v[204:207], v[64:67]
	v_mfma_f32_16x16x32_bf16 v[116:119], v[164:167], v[180:183], v[116:119]
	v_mfma_f32_16x16x32_bf16 v[112:115], v[172:175], v[180:183], v[112:115]
	v_mfma_f32_16x16x32_bf16 v[100:103], v[164:167], v[188:191], v[100:103]
	v_mfma_f32_16x16x32_bf16 v[96:99], v[172:175], v[188:191], v[96:99]
	v_mfma_f32_16x16x32_bf16 v[84:87], v[164:167], v[200:203], v[84:87]
	v_mfma_f32_16x16x32_bf16 v[80:83], v[172:175], v[200:203], v[80:83]
	v_mfma_f32_16x16x32_bf16 v[68:71], v[164:167], v[208:211], v[68:71]
	v_mfma_f32_16x16x32_bf16 v[64:67], v[172:175], v[208:211], v[64:67]
	s_setprio 0
	s_barrier
	s_add_i32 s54, s54, s39
	s_mov_b32 m0, s54
	ds_read_b128 v[176:179], v143 offset:16384
	ds_read_b128 v[180:183], v143 offset:17408
	ds_read_b128 v[184:187], v143 offset:18432
	ds_read_b128 v[188:191], v143 offset:19456
	ds_read_b128 v[196:199], v143 offset:20480
	ds_read_b128 v[200:203], v143 offset:21504
	ds_read_b128 v[204:207], v143 offset:22528
	ds_read_b128 v[208:211], v143 offset:23552
	global_load_lds_dwordx4 v192, s[34:35]
	s_add_i32 m0, s54, 0x2000
	s_add_u32 s54, s34, 0x40000
	s_addc_u32 s55, s35, 0
	s_add_i32 s61, s61, s39
	global_load_lds_dwordx4 v128, s[34:35]
	s_mov_b32 m0, s61
	s_nop 0
	global_load_lds_dwordx4 v192, s[54:55]
	s_add_i32 m0, s61, 0x2000
	s_nop 0
	global_load_lds_dwordx4 v128, s[54:55]
	s_mov_b32 m0, s40
	s_nop 0
	global_load_lds_dwordx4 v132, s[36:37]
	s_mov_b32 m0, s41
	s_nop 0
	global_load_lds_dwordx4 v130, s[36:37]
	s_waitcnt vmcnt(8)
	s_waitcnt lgkmcnt(0)
	s_barrier
	s_setprio 1
	s_waitcnt lgkmcnt(0)
	v_mfma_f32_16x16x32_bf16 v[60:63], v[144:147], v[176:179], v[60:63]
	v_mfma_f32_16x16x32_bf16 v[56:59], v[152:155], v[176:179], v[56:59]
	v_mfma_f32_16x16x32_bf16 v[44:47], v[144:147], v[184:187], v[44:47]
	v_mfma_f32_16x16x32_bf16 v[40:43], v[152:155], v[184:187], v[40:43]
	v_mfma_f32_16x16x32_bf16 v[28:31], v[144:147], v[196:199], v[28:31]
	v_mfma_f32_16x16x32_bf16 v[24:27], v[152:155], v[196:199], v[24:27]
	v_mfma_f32_16x16x32_bf16 v[12:15], v[144:147], v[204:207], v[12:15]
	v_mfma_f32_16x16x32_bf16 v[8:11], v[152:155], v[204:207], v[8:11]
	v_mfma_f32_16x16x32_bf16 v[60:63], v[148:151], v[180:183], v[60:63]
	v_mfma_f32_16x16x32_bf16 v[56:59], v[156:159], v[180:183], v[56:59]
	v_mfma_f32_16x16x32_bf16 v[44:47], v[148:151], v[188:191], v[44:47]
	v_mfma_f32_16x16x32_bf16 v[40:43], v[156:159], v[188:191], v[40:43]
	v_mfma_f32_16x16x32_bf16 v[28:31], v[148:151], v[200:203], v[28:31]
	v_mfma_f32_16x16x32_bf16 v[24:27], v[156:159], v[200:203], v[24:27]
	v_mfma_f32_16x16x32_bf16 v[12:15], v[148:151], v[208:211], v[12:15]
	v_mfma_f32_16x16x32_bf16 v[8:11], v[156:159], v[208:211], v[8:11]
	s_setprio 0
	s_setprio 1
	v_mfma_f32_16x16x32_bf16 v[52:55], v[160:163], v[176:179], v[52:55]
	v_mfma_f32_16x16x32_bf16 v[48:51], v[168:171], v[176:179], v[48:51]
	v_mfma_f32_16x16x32_bf16 v[36:39], v[160:163], v[184:187], v[36:39]
	v_mfma_f32_16x16x32_bf16 v[32:35], v[168:171], v[184:187], v[32:35]
	v_mfma_f32_16x16x32_bf16 v[20:23], v[160:163], v[196:199], v[20:23]
	v_mfma_f32_16x16x32_bf16 v[16:19], v[168:171], v[196:199], v[16:19]
	v_mfma_f32_16x16x32_bf16 v[4:7], v[160:163], v[204:207], v[4:7]
	v_mfma_f32_16x16x32_bf16 v[0:3], v[168:171], v[204:207], v[0:3]
	v_mfma_f32_16x16x32_bf16 v[52:55], v[164:167], v[180:183], v[52:55]
	v_mfma_f32_16x16x32_bf16 v[48:51], v[172:175], v[180:183], v[48:51]
	v_mfma_f32_16x16x32_bf16 v[36:39], v[164:167], v[188:191], v[36:39]
	v_mfma_f32_16x16x32_bf16 v[32:35], v[172:175], v[188:191], v[32:35]
	v_mfma_f32_16x16x32_bf16 v[20:23], v[164:167], v[200:203], v[20:23]
	v_mfma_f32_16x16x32_bf16 v[16:19], v[172:175], v[200:203], v[16:19]
	v_mfma_f32_16x16x32_bf16 v[4:7], v[164:167], v[208:211], v[4:7]
	v_mfma_f32_16x16x32_bf16 v[0:3], v[172:175], v[208:211], v[0:3]
	s_setprio 0
	s_barrier
	s_add_i32 s54, 0, 0x18000
	s_add_i32 s55, 0, 0x1c000
	v_add_u32_e32 v156, s54, v141
	v_add_u32_e32 v172, s55, v141
	ds_read_b128 v[144:147], v156
	ds_read_b128 v[148:151], v156 offset:1024
	ds_read_b128 v[152:155], v156 offset:2048
	ds_read_b128 v[156:159], v156 offset:3072
	ds_read_b128 v[160:163], v172
	ds_read_b128 v[164:167], v172 offset:1024
	ds_read_b128 v[168:171], v172 offset:2048
	ds_read_b128 v[172:175], v172 offset:3072
	s_add_u32 s36, s36, 0x40000
	s_addc_u32 s37, s37, 0
	s_mov_b32 m0, s42
	ds_read_b128 v[176:179], v143 offset:32768
	ds_read_b128 v[180:183], v143 offset:33792
	ds_read_b128 v[184:187], v143 offset:34816
	ds_read_b128 v[188:191], v143 offset:35840
	ds_read_b128 v[196:199], v143 offset:36864
	ds_read_b128 v[200:203], v143 offset:37888
	ds_read_b128 v[204:207], v143 offset:38912
	ds_read_b128 v[208:211], v143 offset:39936
	global_load_lds_dwordx4 v132, s[36:37]
	s_mov_b32 m0, s43
	s_nop 0
	global_load_lds_dwordx4 v130, s[36:37]
	s_waitcnt vmcnt(8)
	s_waitcnt lgkmcnt(0)
	s_barrier
	s_setprio 1
	s_waitcnt lgkmcnt(0)
	v_mfma_f32_16x16x32_bf16 v[124:127], v[144:147], v[176:179], v[124:127]
	v_mfma_f32_16x16x32_bf16 v[120:123], v[152:155], v[176:179], v[120:123]
	v_mfma_f32_16x16x32_bf16 v[108:111], v[144:147], v[184:187], v[108:111]
	v_mfma_f32_16x16x32_bf16 v[104:107], v[152:155], v[184:187], v[104:107]
	v_mfma_f32_16x16x32_bf16 v[92:95], v[144:147], v[196:199], v[92:95]
	v_mfma_f32_16x16x32_bf16 v[88:91], v[152:155], v[196:199], v[88:91]
	v_mfma_f32_16x16x32_bf16 v[76:79], v[144:147], v[204:207], v[76:79]
	v_mfma_f32_16x16x32_bf16 v[72:75], v[152:155], v[204:207], v[72:75]
	v_mfma_f32_16x16x32_bf16 v[124:127], v[148:151], v[180:183], v[124:127]
	v_mfma_f32_16x16x32_bf16 v[120:123], v[156:159], v[180:183], v[120:123]
	v_mfma_f32_16x16x32_bf16 v[108:111], v[148:151], v[188:191], v[108:111]
	v_mfma_f32_16x16x32_bf16 v[104:107], v[156:159], v[188:191], v[104:107]
	v_mfma_f32_16x16x32_bf16 v[92:95], v[148:151], v[200:203], v[92:95]
	v_mfma_f32_16x16x32_bf16 v[88:91], v[156:159], v[200:203], v[88:91]
	v_mfma_f32_16x16x32_bf16 v[76:79], v[148:151], v[208:211], v[76:79]
	v_mfma_f32_16x16x32_bf16 v[72:75], v[156:159], v[208:211], v[72:75]
	s_setprio 0
	s_setprio 1
	v_mfma_f32_16x16x32_bf16 v[116:119], v[160:163], v[176:179], v[116:119]
	v_mfma_f32_16x16x32_bf16 v[112:115], v[168:171], v[176:179], v[112:115]
	v_mfma_f32_16x16x32_bf16 v[100:103], v[160:163], v[184:187], v[100:103]
	v_mfma_f32_16x16x32_bf16 v[96:99], v[168:171], v[184:187], v[96:99]
	v_mfma_f32_16x16x32_bf16 v[84:87], v[160:163], v[196:199], v[84:87]
	v_mfma_f32_16x16x32_bf16 v[80:83], v[168:171], v[196:199], v[80:83]
	v_mfma_f32_16x16x32_bf16 v[68:71], v[160:163], v[204:207], v[68:71]
	v_mfma_f32_16x16x32_bf16 v[64:67], v[168:171], v[204:207], v[64:67]
	v_mfma_f32_16x16x32_bf16 v[116:119], v[164:167], v[180:183], v[116:119]
	v_mfma_f32_16x16x32_bf16 v[112:115], v[172:175], v[180:183], v[112:115]
	v_mfma_f32_16x16x32_bf16 v[100:103], v[164:167], v[188:191], v[100:103]
	v_mfma_f32_16x16x32_bf16 v[96:99], v[172:175], v[188:191], v[96:99]
	v_mfma_f32_16x16x32_bf16 v[84:87], v[164:167], v[200:203], v[84:87]
	v_mfma_f32_16x16x32_bf16 v[80:83], v[172:175], v[200:203], v[80:83]
	v_mfma_f32_16x16x32_bf16 v[68:71], v[164:167], v[208:211], v[68:71]
	v_mfma_f32_16x16x32_bf16 v[64:67], v[172:175], v[208:211], v[64:67]
	s_setprio 0
	s_barrier
	s_add_u32 s36, s36, 0xfffc0080
	s_addc_u32 s37, s37, -1
	s_add_u32 s34, s34, 0x80
	s_addc_u32 s35, s35, 0
	s_add_i32 m0, s54, s39
	ds_read_b128 v[176:179], v143 offset:49152
	ds_read_b128 v[180:183], v143 offset:50176
	ds_read_b128 v[184:187], v143 offset:51200
	ds_read_b128 v[188:191], v143 offset:52224
	ds_read_b128 v[196:199], v143 offset:53248
	ds_read_b128 v[200:203], v143 offset:54272
	ds_read_b128 v[204:207], v143 offset:55296
	ds_read_b128 v[208:211], v143 offset:56320
	global_load_lds_dwordx4 v192, s[34:35]
	s_add_i32 m0, m0, 0x2000
	s_nop 0
	global_load_lds_dwordx4 v128, s[34:35]
	s_add_u32 s34, s34, 0x40000
	s_addc_u32 s35, s35, 0
	s_add_i32 m0, s55, s39
	s_nop 0
	global_load_lds_dwordx4 v192, s[34:35]
	s_add_i32 m0, m0, 0x2000
	s_nop 0
	global_load_lds_dwordx4 v128, s[34:35]
	s_mov_b32 m0, s44
	s_nop 0
	global_load_lds_dwordx4 v132, s[36:37]
	s_mov_b32 m0, s45
	s_nop 0
	global_load_lds_dwordx4 v130, s[36:37]
	s_waitcnt vmcnt(8)
	s_waitcnt lgkmcnt(0)
	s_barrier
	s_setprio 1
	s_waitcnt lgkmcnt(0)
	v_mfma_f32_16x16x32_bf16 v[60:63], v[144:147], v[176:179], v[60:63]
	v_mfma_f32_16x16x32_bf16 v[56:59], v[152:155], v[176:179], v[56:59]
	v_mfma_f32_16x16x32_bf16 v[44:47], v[144:147], v[184:187], v[44:47]
	v_mfma_f32_16x16x32_bf16 v[40:43], v[152:155], v[184:187], v[40:43]
	v_mfma_f32_16x16x32_bf16 v[28:31], v[144:147], v[196:199], v[28:31]
	v_mfma_f32_16x16x32_bf16 v[24:27], v[152:155], v[196:199], v[24:27]
	v_mfma_f32_16x16x32_bf16 v[12:15], v[144:147], v[204:207], v[12:15]
	v_mfma_f32_16x16x32_bf16 v[8:11], v[152:155], v[204:207], v[8:11]
	v_mfma_f32_16x16x32_bf16 v[60:63], v[148:151], v[180:183], v[60:63]
	v_mfma_f32_16x16x32_bf16 v[56:59], v[156:159], v[180:183], v[56:59]
	v_mfma_f32_16x16x32_bf16 v[44:47], v[148:151], v[188:191], v[44:47]
	v_mfma_f32_16x16x32_bf16 v[40:43], v[156:159], v[188:191], v[40:43]
	v_mfma_f32_16x16x32_bf16 v[28:31], v[148:151], v[200:203], v[28:31]
	v_mfma_f32_16x16x32_bf16 v[24:27], v[156:159], v[200:203], v[24:27]
	v_mfma_f32_16x16x32_bf16 v[12:15], v[148:151], v[208:211], v[12:15]
	v_mfma_f32_16x16x32_bf16 v[8:11], v[156:159], v[208:211], v[8:11]
	s_setprio 0
	s_setprio 1
	v_mfma_f32_16x16x32_bf16 v[52:55], v[160:163], v[176:179], v[52:55]
	v_mfma_f32_16x16x32_bf16 v[48:51], v[168:171], v[176:179], v[48:51]
	v_mfma_f32_16x16x32_bf16 v[36:39], v[160:163], v[184:187], v[36:39]
	v_mfma_f32_16x16x32_bf16 v[32:35], v[168:171], v[184:187], v[32:35]
	v_mfma_f32_16x16x32_bf16 v[20:23], v[160:163], v[196:199], v[20:23]
	v_mfma_f32_16x16x32_bf16 v[16:19], v[168:171], v[196:199], v[16:19]
	v_mfma_f32_16x16x32_bf16 v[4:7], v[160:163], v[204:207], v[4:7]
	v_mfma_f32_16x16x32_bf16 v[0:3], v[168:171], v[204:207], v[0:3]
	v_mfma_f32_16x16x32_bf16 v[52:55], v[164:167], v[180:183], v[52:55]
	v_mfma_f32_16x16x32_bf16 v[48:51], v[172:175], v[180:183], v[48:51]
	v_mfma_f32_16x16x32_bf16 v[36:39], v[164:167], v[188:191], v[36:39]
	v_mfma_f32_16x16x32_bf16 v[32:35], v[172:175], v[188:191], v[32:35]
	v_mfma_f32_16x16x32_bf16 v[20:23], v[164:167], v[200:203], v[20:23]
	v_mfma_f32_16x16x32_bf16 v[16:19], v[172:175], v[200:203], v[16:19]
	v_mfma_f32_16x16x32_bf16 v[4:7], v[164:167], v[208:211], v[4:7]
	v_mfma_f32_16x16x32_bf16 v[0:3], v[172:175], v[208:211], v[0:3]
	s_setprio 0
	s_barrier
	s_add_i32 s53, s53, 2
	s_add_u32 s51, s51, 0x100
	s_addc_u32 s52, s52, 0
	s_add_u32 s30, s30, 0x100
	s_addc_u32 s31, s31, 0
	s_cmp_gt_u32 s53, 13
	s_cbranch_scc0 .LBB0_574
	s_and_b64 vcc, exec, s[20:21]
	s_cbranch_vccz .LBB0_577
	s_barrier
